# att19 = att14 + attention mode-1 epilogue: sub-LN gains read from a per-wave LDS copy (filled once per phase) instead of global loads interleaved with the row stores, so the store ladder no longer wai
# baseline (speedup 1.0000x reference)
.LBB0_278:
	v_and_b32_e32 v0, 63, v244
	v_lshlrev_b32_e32 v0, 2, v0
	global_load_dword v2, v0, s[72:73]
	global_load_dword v3, v0, s[74:75]
	global_load_dword v4, v0, s[76:77]
	s_nop 0
	global_load_dword v0, v0, s[78:79]
	v_mbcnt_hi_u32_b32 v5, -1, v145
	v_and_b32_e32 v6, 64, v5
	v_xor_b32_e32 v7, 1, v5
	v_add_u32_e32 v6, 64, v6
	v_cmp_lt_i32_e32 vcc, v7, v6
	v_xor_b32_e32 v8, 2, v5
	v_xor_b32_e32 v9, 4, v5
	v_cndmask_b32_e32 v7, v5, v7, vcc
	v_lshlrev_b32_e32 v232, 2, v7
	v_cmp_lt_i32_e32 vcc, v8, v6
	v_xor_b32_e32 v10, 8, v5
	v_xor_b32_e32 v11, 16, v5
	v_cndmask_b32_e32 v8, v5, v8, vcc
	v_lshlrev_b32_e32 v8, 2, v8
	v_cmp_lt_i32_e32 vcc, v9, v6
	v_xor_b32_e32 v12, 32, v5
	s_add_u32 s94, s22, 0xb000000
	v_cndmask_b32_e32 v9, v5, v9, vcc
	v_cmp_lt_i32_e32 vcc, v10, v6
	s_addc_u32 s95, s23, 0
	s_add_u32 s0, s22, 0xf000000
	v_cndmask_b32_e32 v10, v5, v10, vcc
	v_cmp_lt_i32_e32 vcc, v11, v6
	s_addc_u32 s1, s23, 0
	v_writelane_b32 v254, s0, 35
	s_mov_b32 s7, 0
	v_mov_b32_e32 v1, 0
	v_writelane_b32 v254, s1, 36
	s_add_u32 s0, s22, 0x13000000
	s_addc_u32 s1, s23, 0
	s_add_u32 s86, s20, 0x4000000
	v_writelane_b32 v254, s0, 37
	s_addc_u32 s87, s21, 0
	s_cmpk_lg_i32 s84, 0x100
	v_writelane_b32 v254, s1, 38
	s_cselect_b64 s[96:97], -1, 0
	s_and_b32 s0, s2, 7
	v_writelane_b32 v254, s2, 39
	s_ashr_i32 s1, s2, 3
	v_writelane_b32 v254, s1, 40
	s_xor_b32 s1, s0, 15
	v_writelane_b32 v254, s1, 41
	s_or_b32 s1, s0, 16
	v_writelane_b32 v254, s1, 42
	v_writelane_b32 v254, s0, 43
	s_xor_b32 s0, s0, 31
	v_writelane_b32 v254, s0, 44
	v_writelane_b32 v254, s16, 45
	s_mov_b64 s[8:9], 0x20000
	s_mov_b64 s[10:11], 0x40000
	s_mov_b64 s[12:13], 0x60000
	s_mov_b64 s[14:15], 0x80000
	s_mov_b64 s[42:43], 0x13040000
	s_mov_b64 s[48:49], 0x13040080
	s_mov_b32 s25, 0x41000000
	v_mov_b32_e32 v230, 0x3727c5ac
	v_mov_b32_e32 v231, 0xff800000
	s_mov_b32 s27, 0
	v_writelane_b32 v254, s40, 46
	s_waitcnt vmcnt(2)
	v_mul_f32_e32 v7, v2, v3
	ds_bpermute_b32 v7, v232, v7
	s_waitcnt vmcnt(0)
	v_mul_f32_e32 v13, v4, v0
	ds_bpermute_b32 v13, v232, v13
	v_writelane_b32 v254, s41, 47
	s_waitcnt lgkmcnt(1)
	v_fmac_f32_e32 v7, v2, v3
	v_cndmask_b32_e32 v3, v5, v11, vcc
	s_waitcnt lgkmcnt(0)
	v_fmac_f32_e32 v13, v4, v0
	ds_bpermute_b32 v0, v8, v7
	ds_bpermute_b32 v2, v8, v13
	v_lshlrev_b32_e32 v4, 2, v9
	v_cmp_lt_i32_e32 vcc, v12, v6
	v_lshlrev_b32_e32 v6, 2, v10
	s_waitcnt lgkmcnt(1)
	v_add_f32_e32 v0, v7, v0
	s_waitcnt lgkmcnt(0)
	v_add_f32_e32 v2, v13, v2
	ds_bpermute_b32 v7, v4, v0
	ds_bpermute_b32 v4, v4, v2
	v_lshlrev_b32_e32 v245, 2, v3
	v_cndmask_b32_e32 v5, v5, v12, vcc
	v_lshlrev_b32_e32 v246, 2, v5
	s_waitcnt lgkmcnt(1)
	v_add_f32_e32 v0, v0, v7
	s_waitcnt lgkmcnt(0)
	v_add_f32_e32 v2, v2, v4
	ds_bpermute_b32 v4, v6, v0
	ds_bpermute_b32 v6, v6, v2
	s_waitcnt lgkmcnt(1)
	v_add_f32_e32 v0, v0, v4
	s_waitcnt lgkmcnt(0)
	v_add_f32_e32 v2, v2, v6
	ds_bpermute_b32 v3, v245, v0
	ds_bpermute_b32 v4, v245, v2
	s_waitcnt lgkmcnt(1)
	v_add_f32_e32 v0, v0, v3
	s_waitcnt lgkmcnt(0)
	v_add_f32_e32 v2, v2, v4
	ds_bpermute_b32 v3, v246, v0
	ds_bpermute_b32 v4, v246, v2
	s_waitcnt lgkmcnt(1)
	v_add_f32_e32 v0, v0, v3
	s_waitcnt lgkmcnt(0)
	v_add_f32_e32 v2, v2, v4
	v_mul_f32_e32 v0, 0x3fb8aa3b, v0
	v_mul_f32_e32 v2, 0x3fb8aa3b, v2
	v_exp_f32_e32 v0, v0
	v_exp_f32_e32 v2, v2
	s_nop 0
	v_sub_f32_e32 v0, v0, v2
	v_add_f32_e32 v233, 0x3e4ccccd, v0
	v_and_b32_e32 v208, 31, v244
	v_lshlrev_b32_e32 v208, 4, v208
	global_load_dwordx4 v[204:207], v208, s[80:81]
	v_lshrrev_b32_e32 v209, 6, v244
	v_lshl_add_u32 v208, v209, 9, v208
	v_add_u32_e32 v208, 0x23000, v208
	s_waitcnt vmcnt(0)
	ds_write_b128 v208, v[204:207]
	s_branch .LBB0_281

.LBB0_321:
	v_add_f32_e32 v2, v96, v97
	v_add_f32_e32 v2, v98, v2
	v_add_f32_e32 v2, v99, v2
	v_add_f32_e32 v2, v100, v2
	v_add_f32_e32 v2, v101, v2
	v_add_f32_e32 v2, v102, v2
	v_add_f32_e32 v2, v103, v2
	v_add_f32_e32 v2, v104, v2
	v_add_f32_e32 v2, v105, v2
	v_add_f32_e32 v2, v106, v2
	v_add_f32_e32 v2, v107, v2
	v_add_f32_e32 v2, v108, v2
	v_add_f32_e32 v2, v109, v2
	v_add_f32_e32 v2, v110, v2
	v_add_f32_e32 v2, v111, v2
	v_add_f32_e32 v2, v2, v80
	v_add_f32_e32 v2, v81, v2
	v_add_f32_e32 v2, v82, v2
	v_add_f32_e32 v2, v83, v2
	v_add_f32_e32 v2, v84, v2
	v_add_f32_e32 v2, v85, v2
	v_add_f32_e32 v2, v86, v2
	v_add_f32_e32 v2, v87, v2
	v_add_f32_e32 v2, v88, v2
	v_add_f32_e32 v2, v89, v2
	v_add_f32_e32 v2, v90, v2
	v_add_f32_e32 v2, v91, v2
	v_add_f32_e32 v2, v92, v2
	s_cmp_lg_u32 0, -1
	v_add_f32_e32 v2, v93, v2
	s_cselect_b32 s0, 0, 0
	v_add_f32_e32 v2, v94, v2
	s_addk_i32 s0, 0x6000
	v_add_f32_e32 v2, v95, v2
	v_add3_u32 v3, v241, s0, v238
	v_add_f32_e32 v2, v14, v2
	v_cvt_pk_bf16_f32 v4, v96, v97
	v_cvt_pk_bf16_f32 v5, v98, v99
	v_cvt_pk_bf16_f32 v6, v100, v101
	v_cvt_pk_bf16_f32 v7, v102, v103
	v_cvt_pk_bf16_f32 v8, v104, v105
	v_cvt_pk_bf16_f32 v9, v106, v107
	v_cvt_pk_bf16_f32 v10, v108, v109
	v_cvt_pk_bf16_f32 v11, v110, v111
	v_cvt_pk_bf16_f32 v12, v80, v81
	v_cvt_pk_bf16_f32 v13, v82, v83
	v_cvt_pk_bf16_f32 v14, v84, v85
	v_cvt_pk_bf16_f32 v15, v86, v87
	v_cvt_pk_bf16_f32 v80, v88, v89
	v_cvt_pk_bf16_f32 v81, v90, v91
	v_cvt_pk_bf16_f32 v82, v92, v93
	v_cvt_pk_bf16_f32 v83, v94, v95
	s_lshl_b32 s0, s50, 1
	v_add3_u32 v3, v3, v239, s0
	ds_read_b64_tr_b16 v[84:85],v3 offset:0
	ds_read_b64_tr_b16 v[86:87],v3 offset:512
	ds_read_b64_tr_b16 v[88:89],v3 offset:1024
	ds_read_b64_tr_b16 v[90:91],v3 offset:1536
	ds_read_b64_tr_b16 v[92:93],v3 offset:2048
	ds_read_b64_tr_b16 v[94:95],v3 offset:2560
	ds_read_b64_tr_b16 v[96:97],v3 offset:3072
	ds_read_b64_tr_b16 v[98:99],v3 offset:3584
	s_waitcnt lgkmcnt(0)
	s_nop 0
	v_mfma_f32_32x32x16_bf16 v[16:31], v[4:7], v[84:87], v[16:31]
	ds_read_b64_tr_b16 v[84:85],v3 offset:4096
	ds_read_b64_tr_b16 v[86:87],v3 offset:4608
	v_mfma_f32_32x32x16_bf16 v[16:31], v[8:11], v[88:91], v[16:31]
	ds_read_b64_tr_b16 v[88:89],v3 offset:5120
	ds_read_b64_tr_b16 v[90:91],v3 offset:5632
	v_mfma_f32_32x32x16_bf16 v[16:31], v[12:15], v[92:95], v[16:31]
	ds_read_b64_tr_b16 v[92:93],v3 offset:6144
	ds_read_b64_tr_b16 v[94:95],v3 offset:6656
	v_mfma_f32_32x32x16_bf16 v[16:31], v[80:83], v[96:99], v[16:31]
	ds_read_b64_tr_b16 v[96:97],v3 offset:7168
	ds_read_b64_tr_b16 v[98:99],v3 offset:7680
	s_waitcnt lgkmcnt(0)
	v_mfma_f32_32x32x16_bf16 v[32:47], v[4:7], v[84:87], v[32:47]
	v_add_u32_e32 v3, 0x2000, v3
	ds_read_b64_tr_b16 v[84:85],v3 offset:0
	ds_read_b64_tr_b16 v[86:87],v3 offset:512
	v_mfma_f32_32x32x16_bf16 v[32:47], v[8:11], v[88:91], v[32:47]
	ds_read_b64_tr_b16 v[88:89],v3 offset:1024
	ds_read_b64_tr_b16 v[90:91],v3 offset:1536
	v_mfma_f32_32x32x16_bf16 v[32:47], v[12:15], v[92:95], v[32:47]
	ds_read_b64_tr_b16 v[92:93],v3 offset:2048
	ds_read_b64_tr_b16 v[94:95],v3 offset:2560
	v_mfma_f32_32x32x16_bf16 v[32:47], v[80:83], v[96:99], v[32:47]
	ds_read_b64_tr_b16 v[96:97],v3 offset:3072
	ds_read_b64_tr_b16 v[98:99],v3 offset:3584
	s_waitcnt lgkmcnt(0)
	v_mfma_f32_32x32x16_bf16 v[48:63], v[4:7], v[84:87], v[48:63]
	ds_read_b64_tr_b16 v[84:85],v3 offset:4096
	ds_read_b64_tr_b16 v[86:87],v3 offset:4608
	v_mfma_f32_32x32x16_bf16 v[48:63], v[8:11], v[88:91], v[48:63]
	ds_read_b64_tr_b16 v[88:89],v3 offset:5120
	ds_read_b64_tr_b16 v[90:91],v3 offset:5632
	v_mfma_f32_32x32x16_bf16 v[48:63], v[12:15], v[92:95], v[48:63]
	ds_read_b64_tr_b16 v[92:93],v3 offset:6144
	ds_read_b64_tr_b16 v[94:95],v3 offset:6656
	v_mfma_f32_32x32x16_bf16 v[48:63], v[80:83], v[96:99], v[48:63]
	ds_read_b64_tr_b16 v[96:97],v3 offset:7168
	ds_read_b64_tr_b16 v[98:99],v3 offset:7680
	s_waitcnt lgkmcnt(0)
	v_mfma_f32_32x32x16_bf16 v[64:79], v[4:7], v[84:87], v[64:79]
	v_mov_b32_e32 v3, v2
	s_nop 1
	v_permlane32_swap_b32_e32 v2, v3
	v_cmp_gt_u32_e32 vcc, 32, v235
	v_mfma_f32_32x32x16_bf16 v[64:79], v[8:11], v[88:91], v[64:79]
	v_mfma_f32_32x32x16_bf16 v[64:79], v[12:15], v[92:95], v[64:79]
	v_mfma_f32_32x32x16_bf16 v[64:79], v[80:83], v[96:99], v[64:79]
	s_and_saveexec_b64 s[0:1], vcc
	v_add_f32_e32 v2, v2, v3
	ds_write_b32 v240, v2 offset:128
	s_or_b64 exec, exec, s[0:1]
	s_waitcnt lgkmcnt(0)
	ds_read_b128 v[2:5], v0 offset:128
	ds_read_b128 v[6:9], v0 offset:160
	s_lshl_b32 s0, s44, 13
	s_add_i32 s2, s0, 0
	s_add_i32 s2, s2, 0x12800
	s_waitcnt lgkmcnt(1)
	v_rcp_f32_e32 v10, v2
	v_rcp_f32_e32 v11, v3
	v_rcp_f32_e32 v12, v4
	v_rcp_f32_e32 v13, v5
	s_waitcnt lgkmcnt(0)
	v_rcp_f32_e32 v14, v6
	ds_read_b128 v[2:5], v0 offset:192
	v_rcp_f32_e32 v15, v7
	v_rcp_f32_e32 v81, v8
	v_rcp_f32_e32 v82, v9
	ds_read_b128 v[6:9], v0 offset:224
	s_waitcnt lgkmcnt(1)
	v_rcp_f32_e32 v0, v2
	v_rcp_f32_e32 v2, v3
	v_rcp_f32_e32 v3, v4
	v_rcp_f32_e32 v4, v5
	s_waitcnt lgkmcnt(0)
	v_rcp_f32_e32 v5, v6
	v_rcp_f32_e32 v6, v7
	v_rcp_f32_e32 v7, v8
	v_rcp_f32_e32 v8, v9
	v_lshlrev_b32_e32 v131, 8, v237
	s_mov_b64 s[0:1], -1
	s_andn2_b64 vcc, exec, s[72:73]
	v_lshl_add_u32 v80, v236, 1, s2
	v_mul_f32_e32 v133, v16, v10
	v_mul_f32_e32 v132, v32, v10
	v_mul_f32_e32 v130, v48, v10
	v_mul_f32_e32 v129, v64, v10
	v_mul_f32_e32 v128, v17, v11
	v_mul_f32_e32 v127, v33, v11
	v_mul_f32_e32 v126, v49, v11
	v_mul_f32_e32 v125, v65, v11
	v_mul_f32_e32 v124, v18, v12
	v_mul_f32_e32 v123, v34, v12
	v_mul_f32_e32 v122, v50, v12
	v_mul_f32_e32 v121, v66, v12
	v_mul_f32_e32 v120, v19, v13
	v_mul_f32_e32 v119, v35, v13
	v_mul_f32_e32 v118, v51, v13
	v_mul_f32_e32 v117, v67, v13
	v_or_b32_e32 v115, 0x800, v131
	v_mul_f32_e32 v116, v20, v14
	v_mul_f32_e32 v114, v36, v14
	v_mul_f32_e32 v113, v52, v14
	v_mul_f32_e32 v112, v68, v14
	v_or_b32_e32 v110, 0x900, v131
	v_mul_f32_e32 v111, v21, v15
	v_mul_f32_e32 v109, v37, v15
	v_mul_f32_e32 v108, v53, v15
	v_mul_f32_e32 v107, v69, v15
	v_or_b32_e32 v105, 0xa00, v131
	v_mul_f32_e32 v106, v22, v81
	v_mul_f32_e32 v104, v38, v81
	v_mul_f32_e32 v103, v54, v81
	v_mul_f32_e32 v102, v70, v81
	v_or_b32_e32 v100, 0xb00, v131
	v_mul_f32_e32 v101, v23, v82
	v_mul_f32_e32 v99, v39, v82
	v_mul_f32_e32 v98, v55, v82
	v_mul_f32_e32 v97, v71, v82
	v_or_b32_e32 v95, 0x1000, v131
	v_mul_f32_e32 v96, v24, v0
	v_mul_f32_e32 v94, v40, v0
	v_mul_f32_e32 v93, v56, v0
	v_mul_f32_e32 v92, v72, v0
	v_or_b32_e32 v90, 0x1100, v131
	v_mul_f32_e32 v91, v25, v2
	v_mul_f32_e32 v89, v41, v2
	v_mul_f32_e32 v88, v57, v2
	v_mul_f32_e32 v87, v73, v2
	v_or_b32_e32 v85, 0x1200, v131
	v_mul_f32_e32 v86, v26, v3
	v_mul_f32_e32 v84, v42, v3
	v_mul_f32_e32 v83, v58, v3
	v_mul_f32_e32 v82, v74, v3
	v_or_b32_e32 v74, 0x1300, v131
	v_mul_f32_e32 v81, v27, v4
	v_mul_f32_e32 v73, v43, v4
	v_mul_f32_e32 v72, v59, v4
	v_mul_f32_e32 v71, v75, v4
	v_or_b32_e32 v69, 0x1800, v131
	v_mul_f32_e32 v70, v28, v5
	v_mul_f32_e32 v68, v44, v5
	v_mul_f32_e32 v67, v60, v5
	v_mul_f32_e32 v66, v76, v5
	v_or_b32_e32 v64, 0x1900, v131
	v_mul_f32_e32 v65, v29, v6
	v_mul_f32_e32 v60, v45, v6
	v_mul_f32_e32 v59, v61, v6
	v_mul_f32_e32 v58, v77, v6
	v_or_b32_e32 v56, 0x1a00, v131
	v_mul_f32_e32 v57, v30, v7
	v_mul_f32_e32 v55, v46, v7
	v_mul_f32_e32 v54, v62, v7
	v_mul_f32_e32 v53, v78, v7
	v_or_b32_e32 v51, 0x1b00, v131
	v_mul_f32_e32 v52, v31, v8
	v_mul_f32_e32 v50, v47, v8
	v_mul_f32_e32 v49, v63, v8
	v_mul_f32_e32 v48, v79, v8
	s_cbranch_vccnz .LBB0_325
	v_add_u32_e32 v0, v80, v131
	ds_read_u16 v2, v0
	ds_read_u16 v3, v0 offset:64
	ds_read_u16 v4, v0 offset:128
	ds_read_u16 v5, v0 offset:192
	ds_read_u16 v6, v0 offset:256
	ds_read_u16 v7, v0 offset:320
	ds_read_u16 v8, v0 offset:384
	ds_read_u16 v9, v0 offset:448
	s_waitcnt lgkmcnt(7)
	v_lshlrev_b32_e32 v2, 16, v2
	v_fma_f32 v2, -v233, v133, v2
	v_cvt_pk_bf16_f32 v2, v2, s0
	ds_write_b16 v0, v2
	s_waitcnt lgkmcnt(7)
	v_lshlrev_b32_e32 v2, 16, v3
	v_fma_f32 v2, -v233, v132, v2
	v_cvt_pk_bf16_f32 v2, v2, s0
	ds_write_b16 v0, v2 offset:64
	s_waitcnt lgkmcnt(7)
	v_lshlrev_b32_e32 v2, 16, v4
	v_fma_f32 v2, -v233, v130, v2
	v_cvt_pk_bf16_f32 v2, v2, s0
	ds_write_b16 v0, v2 offset:128
	s_waitcnt lgkmcnt(7)
	v_lshlrev_b32_e32 v2, 16, v5
	v_fma_f32 v2, -v233, v129, v2
	v_cvt_pk_bf16_f32 v2, v2, s0
	ds_write_b16 v0, v2 offset:192
	s_waitcnt lgkmcnt(7)
	v_lshlrev_b32_e32 v2, 16, v6
	v_fma_f32 v2, -v233, v128, v2
	v_cvt_pk_bf16_f32 v2, v2, s0
	ds_write_b16 v0, v2 offset:256
	s_waitcnt lgkmcnt(7)
	v_lshlrev_b32_e32 v2, 16, v7
	v_fma_f32 v2, -v233, v127, v2
	v_cvt_pk_bf16_f32 v2, v2, s0
	ds_write_b16 v0, v2 offset:320
	s_waitcnt lgkmcnt(7)
	v_lshlrev_b32_e32 v2, 16, v8
	v_fma_f32 v2, -v233, v126, v2
	v_cvt_pk_bf16_f32 v2, v2, s0
	ds_write_b16 v0, v2 offset:384
	s_waitcnt lgkmcnt(7)
	v_lshlrev_b32_e32 v2, 16, v9
	v_fma_f32 v2, -v233, v125, v2
	v_cvt_pk_bf16_f32 v2, v2, s0
	ds_write_b16 v0, v2 offset:448
	ds_read_u16 v2, v0 offset:512
	ds_read_u16 v3, v0 offset:576
	ds_read_u16 v4, v0 offset:640
	ds_read_u16 v5, v0 offset:704
	ds_read_u16 v6, v0 offset:768
	ds_read_u16 v7, v0 offset:832
	ds_read_u16 v8, v0 offset:896
	ds_read_u16 v9, v0 offset:960
	s_waitcnt lgkmcnt(7)
	v_lshlrev_b32_e32 v2, 16, v2
	v_fma_f32 v2, -v233, v124, v2
	v_cvt_pk_bf16_f32 v2, v2, s0
	ds_write_b16 v0, v2 offset:512
	s_waitcnt lgkmcnt(7)
	v_lshlrev_b32_e32 v2, 16, v3
	v_fma_f32 v2, -v233, v123, v2
	v_cvt_pk_bf16_f32 v2, v2, s0
	ds_write_b16 v0, v2 offset:576
	s_waitcnt lgkmcnt(7)
	v_lshlrev_b32_e32 v2, 16, v4
	v_fma_f32 v2, -v233, v122, v2
	v_cvt_pk_bf16_f32 v2, v2, s0
	ds_write_b16 v0, v2 offset:640
	s_waitcnt lgkmcnt(7)
	v_lshlrev_b32_e32 v2, 16, v5
	v_fma_f32 v2, -v233, v121, v2
	v_cvt_pk_bf16_f32 v2, v2, s0
	ds_write_b16 v0, v2 offset:704
	s_waitcnt lgkmcnt(7)
	v_lshlrev_b32_e32 v2, 16, v6
	v_fma_f32 v2, -v233, v120, v2
	v_cvt_pk_bf16_f32 v2, v2, s0
	ds_write_b16 v0, v2 offset:768
	s_waitcnt lgkmcnt(7)
	v_lshlrev_b32_e32 v2, 16, v7
	v_fma_f32 v2, -v233, v119, v2
	v_cvt_pk_bf16_f32 v2, v2, s0
	ds_write_b16 v0, v2 offset:832
	s_waitcnt lgkmcnt(7)
	v_lshlrev_b32_e32 v2, 16, v8
	v_fma_f32 v2, -v233, v118, v2
	v_cvt_pk_bf16_f32 v2, v2, s0
	ds_write_b16 v0, v2 offset:896
	s_waitcnt lgkmcnt(7)
	v_lshlrev_b32_e32 v2, 16, v9
	v_fma_f32 v2, -v233, v117, v2
	v_cvt_pk_bf16_f32 v2, v2, s0
	ds_write_b16 v0, v2 offset:960
	v_add_u32_e32 v0, v80, v115
	ds_read_u16 v2, v0
	ds_read_u16 v3, v0 offset:64
	ds_read_u16 v4, v0 offset:128
	ds_read_u16 v5, v0 offset:192
	v_lshrrev_b32_e32 v47, 1, v235
	s_waitcnt lgkmcnt(3)
	v_lshlrev_b32_e32 v2, 16, v2
	v_fma_f32 v2, -v233, v116, v2
	v_cvt_pk_bf16_f32 v2, v2, s0
	ds_write_b16 v0, v2
	s_waitcnt lgkmcnt(3)
	v_lshlrev_b32_e32 v2, 16, v3
	v_fma_f32 v2, -v233, v114, v2
	v_cvt_pk_bf16_f32 v2, v2, s0
	ds_write_b16 v0, v2 offset:64
	s_waitcnt lgkmcnt(3)
	v_lshlrev_b32_e32 v2, 16, v4
	v_fma_f32 v2, -v233, v113, v2
	v_cvt_pk_bf16_f32 v2, v2, s0
	ds_write_b16 v0, v2 offset:128
	s_waitcnt lgkmcnt(3)
	v_lshlrev_b32_e32 v2, 16, v5
	v_fma_f32 v2, -v233, v112, v2
	v_cvt_pk_bf16_f32 v2, v2, s0
	ds_write_b16 v0, v2 offset:192
	v_add_u32_e32 v0, v80, v110
	ds_read_u16 v2, v0
	ds_read_u16 v3, v0 offset:64
	ds_read_u16 v4, v0 offset:128
	ds_read_u16 v5, v0 offset:192
	s_waitcnt lgkmcnt(3)
	v_lshlrev_b32_e32 v2, 16, v2
	v_fma_f32 v2, -v233, v111, v2
	v_cvt_pk_bf16_f32 v2, v2, s0
	ds_write_b16 v0, v2
	s_waitcnt lgkmcnt(3)
	v_lshlrev_b32_e32 v2, 16, v3
	v_fma_f32 v2, -v233, v109, v2
	v_cvt_pk_bf16_f32 v2, v2, s0
	ds_write_b16 v0, v2 offset:64
	s_waitcnt lgkmcnt(3)
	v_lshlrev_b32_e32 v2, 16, v4
	v_fma_f32 v2, -v233, v108, v2
	v_cvt_pk_bf16_f32 v2, v2, s0
	ds_write_b16 v0, v2 offset:128
	s_waitcnt lgkmcnt(3)
	v_lshlrev_b32_e32 v2, 16, v5
	v_fma_f32 v2, -v233, v107, v2
	v_cvt_pk_bf16_f32 v2, v2, s0
	ds_write_b16 v0, v2 offset:192
	v_add_u32_e32 v0, v80, v105
	ds_read_u16 v2, v0
	ds_read_u16 v3, v0 offset:64
	ds_read_u16 v4, v0 offset:128
	ds_read_u16 v5, v0 offset:192
	s_waitcnt lgkmcnt(3)
	v_lshlrev_b32_e32 v2, 16, v2
	v_fma_f32 v2, -v233, v106, v2
	v_cvt_pk_bf16_f32 v2, v2, s0
	ds_write_b16 v0, v2
	s_waitcnt lgkmcnt(3)
	v_lshlrev_b32_e32 v2, 16, v3
	v_fma_f32 v2, -v233, v104, v2
	v_cvt_pk_bf16_f32 v2, v2, s0
	ds_write_b16 v0, v2 offset:64
	s_waitcnt lgkmcnt(3)
	v_lshlrev_b32_e32 v2, 16, v4
	v_fma_f32 v2, -v233, v103, v2
	v_cvt_pk_bf16_f32 v2, v2, s0
	ds_write_b16 v0, v2 offset:128
	s_waitcnt lgkmcnt(3)
	v_lshlrev_b32_e32 v2, 16, v5
	v_fma_f32 v2, -v233, v102, v2
	v_cvt_pk_bf16_f32 v2, v2, s0
	ds_write_b16 v0, v2 offset:192
	v_add_u32_e32 v0, v80, v100
	ds_read_u16 v2, v0
	ds_read_u16 v3, v0 offset:64
	ds_read_u16 v4, v0 offset:128
	ds_read_u16 v5, v0 offset:192
	s_waitcnt lgkmcnt(3)
	v_lshlrev_b32_e32 v2, 16, v2
	v_fma_f32 v2, -v233, v101, v2
	v_cvt_pk_bf16_f32 v2, v2, s0
	ds_write_b16 v0, v2
	s_waitcnt lgkmcnt(3)
	v_lshlrev_b32_e32 v2, 16, v3
	v_fma_f32 v2, -v233, v99, v2
	v_cvt_pk_bf16_f32 v2, v2, s0
	ds_write_b16 v0, v2 offset:64
	s_waitcnt lgkmcnt(3)
	v_lshlrev_b32_e32 v2, 16, v4
	v_fma_f32 v2, -v233, v98, v2
	v_cvt_pk_bf16_f32 v2, v2, s0
	ds_write_b16 v0, v2 offset:128
	s_waitcnt lgkmcnt(3)
	v_lshlrev_b32_e32 v2, 16, v5
	v_fma_f32 v2, -v233, v97, v2
	v_cvt_pk_bf16_f32 v2, v2, s0
	ds_write_b16 v0, v2 offset:192
	v_add_u32_e32 v0, v80, v95
	ds_read_u16 v2, v0
	ds_read_u16 v3, v0 offset:64
	ds_read_u16 v4, v0 offset:128
	ds_read_u16 v5, v0 offset:192
	s_waitcnt lgkmcnt(3)
	v_lshlrev_b32_e32 v2, 16, v2
	v_fma_f32 v2, -v233, v96, v2
	v_cvt_pk_bf16_f32 v2, v2, s0
	ds_write_b16 v0, v2
	s_waitcnt lgkmcnt(3)
	v_lshlrev_b32_e32 v2, 16, v3
	v_fma_f32 v2, -v233, v94, v2
	v_cvt_pk_bf16_f32 v2, v2, s0
	ds_write_b16 v0, v2 offset:64
	s_waitcnt lgkmcnt(3)
	v_lshlrev_b32_e32 v2, 16, v4
	v_fma_f32 v2, -v233, v93, v2
	v_cvt_pk_bf16_f32 v2, v2, s0
	ds_write_b16 v0, v2 offset:128
	s_waitcnt lgkmcnt(3)
	v_lshlrev_b32_e32 v2, 16, v5
	v_fma_f32 v2, -v233, v92, v2
	v_cvt_pk_bf16_f32 v2, v2, s0
	ds_write_b16 v0, v2 offset:192
	v_add_u32_e32 v0, v80, v90
	ds_read_u16 v2, v0
	ds_read_u16 v3, v0 offset:64
	ds_read_u16 v4, v0 offset:128
	ds_read_u16 v5, v0 offset:192
	s_waitcnt lgkmcnt(3)
	v_lshlrev_b32_e32 v2, 16, v2
	v_fma_f32 v2, -v233, v91, v2
	v_cvt_pk_bf16_f32 v2, v2, s0
	ds_write_b16 v0, v2
	s_waitcnt lgkmcnt(3)
	v_lshlrev_b32_e32 v2, 16, v3
	v_fma_f32 v2, -v233, v89, v2
	v_cvt_pk_bf16_f32 v2, v2, s0
	ds_write_b16 v0, v2 offset:64
	s_waitcnt lgkmcnt(3)
	v_lshlrev_b32_e32 v2, 16, v4
	v_fma_f32 v2, -v233, v88, v2
	v_cvt_pk_bf16_f32 v2, v2, s0
	ds_write_b16 v0, v2 offset:128
	s_waitcnt lgkmcnt(3)
	v_lshlrev_b32_e32 v2, 16, v5
	v_fma_f32 v2, -v233, v87, v2
	v_cvt_pk_bf16_f32 v2, v2, s0
	ds_write_b16 v0, v2 offset:192
	v_add_u32_e32 v0, v80, v85
	ds_read_u16 v2, v0
	ds_read_u16 v3, v0 offset:64
	ds_read_u16 v4, v0 offset:128
	ds_read_u16 v5, v0 offset:192
	s_waitcnt lgkmcnt(3)
	v_lshlrev_b32_e32 v2, 16, v2
	v_fma_f32 v2, -v233, v86, v2
	v_cvt_pk_bf16_f32 v2, v2, s0
	ds_write_b16 v0, v2
	s_waitcnt lgkmcnt(3)
	v_lshlrev_b32_e32 v2, 16, v3
	v_fma_f32 v2, -v233, v84, v2
	v_cvt_pk_bf16_f32 v2, v2, s0
	ds_write_b16 v0, v2 offset:64
	s_waitcnt lgkmcnt(3)
	v_lshlrev_b32_e32 v2, 16, v4
	v_fma_f32 v2, -v233, v83, v2
	v_cvt_pk_bf16_f32 v2, v2, s0
	ds_write_b16 v0, v2 offset:128
	s_waitcnt lgkmcnt(3)
	v_lshlrev_b32_e32 v2, 16, v5
	v_fma_f32 v2, -v233, v82, v2
	v_cvt_pk_bf16_f32 v2, v2, s0
	ds_write_b16 v0, v2 offset:192
	v_add_u32_e32 v0, v80, v74
	ds_read_u16 v2, v0
	ds_read_u16 v3, v0 offset:64
	ds_read_u16 v4, v0 offset:128
	ds_read_u16 v5, v0 offset:192
	s_waitcnt lgkmcnt(3)
	v_lshlrev_b32_e32 v2, 16, v2
	v_fma_f32 v2, -v233, v81, v2
	v_cvt_pk_bf16_f32 v2, v2, s0
	ds_write_b16 v0, v2
	s_waitcnt lgkmcnt(3)
	v_lshlrev_b32_e32 v2, 16, v3
	v_fma_f32 v2, -v233, v73, v2
	v_cvt_pk_bf16_f32 v2, v2, s0
	ds_write_b16 v0, v2 offset:64
	s_waitcnt lgkmcnt(3)
	v_lshlrev_b32_e32 v2, 16, v4
	v_fma_f32 v2, -v233, v72, v2
	v_cvt_pk_bf16_f32 v2, v2, s0
	ds_write_b16 v0, v2 offset:128
	s_waitcnt lgkmcnt(3)
	v_lshlrev_b32_e32 v2, 16, v5
	v_fma_f32 v2, -v233, v71, v2
	v_cvt_pk_bf16_f32 v2, v2, s0
	ds_write_b16 v0, v2 offset:192
	v_add_u32_e32 v0, v80, v69
	ds_read_u16 v2, v0
	ds_read_u16 v3, v0 offset:64
	ds_read_u16 v4, v0 offset:128
	ds_read_u16 v5, v0 offset:192
	s_waitcnt lgkmcnt(3)
	v_lshlrev_b32_e32 v2, 16, v2
	v_fma_f32 v2, -v233, v70, v2
	v_cvt_pk_bf16_f32 v2, v2, s0
	ds_write_b16 v0, v2
	s_waitcnt lgkmcnt(3)
	v_lshlrev_b32_e32 v2, 16, v3
	v_fma_f32 v2, -v233, v68, v2
	v_cvt_pk_bf16_f32 v2, v2, s0
	ds_write_b16 v0, v2 offset:64
	s_waitcnt lgkmcnt(3)
	v_lshlrev_b32_e32 v2, 16, v4
	v_fma_f32 v2, -v233, v67, v2
	v_cvt_pk_bf16_f32 v2, v2, s0
	ds_write_b16 v0, v2 offset:128
	s_waitcnt lgkmcnt(3)
	v_lshlrev_b32_e32 v2, 16, v5
	v_fma_f32 v2, -v233, v66, v2
	v_cvt_pk_bf16_f32 v2, v2, s0
	ds_write_b16 v0, v2 offset:192
	v_add_u32_e32 v0, v80, v64
	ds_read_u16 v2, v0
	ds_read_u16 v3, v0 offset:64
	ds_read_u16 v4, v0 offset:128
	ds_read_u16 v5, v0 offset:192
	s_waitcnt lgkmcnt(3)
	v_lshlrev_b32_e32 v2, 16, v2
	v_fma_f32 v2, -v233, v65, v2
	v_cvt_pk_bf16_f32 v2, v2, s0
	ds_write_b16 v0, v2
	s_waitcnt lgkmcnt(3)
	v_lshlrev_b32_e32 v2, 16, v3
	v_fma_f32 v2, -v233, v60, v2
	v_cvt_pk_bf16_f32 v2, v2, s0
	ds_write_b16 v0, v2 offset:64
	s_waitcnt lgkmcnt(3)
	v_lshlrev_b32_e32 v2, 16, v4
	v_fma_f32 v2, -v233, v59, v2
	v_cvt_pk_bf16_f32 v2, v2, s0
	ds_write_b16 v0, v2 offset:128
	s_waitcnt lgkmcnt(3)
	v_lshlrev_b32_e32 v2, 16, v5
	v_fma_f32 v2, -v233, v58, v2
	v_cvt_pk_bf16_f32 v2, v2, s0
	ds_write_b16 v0, v2 offset:192
	v_add_u32_e32 v0, v80, v56
	ds_read_u16 v2, v0
	ds_read_u16 v3, v0 offset:64
	ds_read_u16 v4, v0 offset:128
	ds_read_u16 v5, v0 offset:192
	s_waitcnt lgkmcnt(3)
	v_lshlrev_b32_e32 v2, 16, v2
	v_fma_f32 v2, -v233, v57, v2
	v_cvt_pk_bf16_f32 v2, v2, s0
	ds_write_b16 v0, v2
	s_waitcnt lgkmcnt(3)
	v_lshlrev_b32_e32 v2, 16, v3
	v_fma_f32 v2, -v233, v55, v2
	v_cvt_pk_bf16_f32 v2, v2, s0
	ds_write_b16 v0, v2 offset:64
	s_waitcnt lgkmcnt(3)
	v_lshlrev_b32_e32 v2, 16, v4
	v_fma_f32 v2, -v233, v54, v2
	v_cvt_pk_bf16_f32 v2, v2, s0
	ds_write_b16 v0, v2 offset:128
	s_waitcnt lgkmcnt(3)
	v_lshlrev_b32_e32 v2, 16, v5
	v_fma_f32 v2, -v233, v53, v2
	v_cvt_pk_bf16_f32 v2, v2, s0
	ds_write_b16 v0, v2 offset:192
	v_add_u32_e32 v0, v80, v51
	ds_read_u16 v2, v0
	ds_read_u16 v3, v0 offset:64
	ds_read_u16 v4, v0 offset:128
	ds_read_u16 v5, v0 offset:192
	s_waitcnt lgkmcnt(3)
	v_lshlrev_b32_e32 v2, 16, v2
	v_fma_f32 v2, -v233, v52, v2
	v_cvt_pk_bf16_f32 v2, v2, s0
	ds_write_b16 v0, v2
	s_waitcnt lgkmcnt(3)
	v_lshlrev_b32_e32 v2, 16, v3
	v_fma_f32 v2, -v233, v50, v2
	v_cvt_pk_bf16_f32 v2, v2, s0
	ds_write_b16 v0, v2 offset:64
	s_waitcnt lgkmcnt(3)
	v_lshlrev_b32_e32 v2, 16, v4
	v_fma_f32 v2, -v233, v49, v2
	v_cvt_pk_bf16_f32 v2, v2, s0
	ds_write_b16 v0, v2 offset:128
	s_waitcnt lgkmcnt(3)
	v_lshlrev_b32_e32 v2, 16, v5
	v_fma_f32 v2, -v233, v48, v2
	v_cvt_pk_bf16_f32 v2, v2, s0
	ds_write_b16 v0, v2 offset:192
	v_lshlrev_b32_e32 v2, 6, v234
	v_and_b32_e32 v61, 64, v2
	v_lshlrev_b32_e32 v0, 8, v47
	v_lshlrev_b32_e32 v46, 1, v61
	s_waitcnt lgkmcnt(0)
	v_add3_u32 v75, s2, v0, v46
	ds_read_b128 v[6:9], v75 offset:16
	ds_read_b128 v[38:41], v75
	ds_read_b128 v[42:45], v75 offset:32
	ds_read_b128 v[2:5], v75 offset:48
	ds_read_b128 v[76:79], v75 offset:80
	s_waitcnt lgkmcnt(4)
	v_and_b32_e32 v31, 0xffff0000, v7
	v_and_b32_e32 v30, 0xffff0000, v6
	v_lshlrev_b32_e32 v35, 16, v7
	v_lshlrev_b32_e32 v34, 16, v6
	v_pk_mul_f32 v[6:7], v[30:31], v[30:31]
	v_and_b32_e32 v33, 0xffff0000, v9
	v_and_b32_e32 v32, 0xffff0000, v8
	v_pk_fma_f32 v[6:7], v[34:35], v[34:35], v[6:7]
	v_lshlrev_b32_e32 v37, 16, v9
	v_lshlrev_b32_e32 v36, 16, v8
	v_pk_mul_f32 v[8:9], v[32:33], v[32:33]
	v_pk_add_f32 v[6:7], v[6:7], v[6:7] op_sel:[0,1] op_sel_hi:[1,0]
	v_pk_fma_f32 v[8:9], v[36:37], v[36:37], v[8:9]
	s_waitcnt lgkmcnt(0)
	v_lshlrev_b32_e32 v13, 16, v77
	v_pk_add_f32 v[6:7], v[8:9], v[6:7]
	v_lshlrev_b32_e32 v12, 16, v76
	v_pk_add_f32 v[62:63], v[8:9], v[6:7] op_sel:[1,0] op_sel_hi:[0,1]
	ds_read_b128 v[6:9], v75 offset:64
	v_lshlrev_b32_e32 v61, 2, v61
	v_lshlrev_b32_e32 v21, 16, v79
	v_lshlrev_b32_e32 v20, 16, v78
	ds_read_b128 v[134:137], v75 offset:112
	s_waitcnt lgkmcnt(1)
	v_and_b32_e32 v17, 0xffff0000, v7
	v_and_b32_e32 v16, 0xffff0000, v6
	v_lshlrev_b32_e32 v23, 16, v7
	v_lshlrev_b32_e32 v22, 16, v6
	v_pk_mul_f32 v[6:7], v[16:17], v[16:17]
	v_and_b32_e32 v19, 0xffff0000, v9
	v_and_b32_e32 v18, 0xffff0000, v8
	v_pk_fma_f32 v[6:7], v[22:23], v[22:23], v[6:7]
	v_lshlrev_b32_e32 v25, 16, v9
	v_lshlrev_b32_e32 v24, 16, v8
	v_pk_mul_f32 v[8:9], v[18:19], v[18:19]
	v_pk_add_f32 v[6:7], v[6:7], v[6:7] op_sel:[0,1] op_sel_hi:[1,0]
	v_pk_fma_f32 v[8:9], v[24:25], v[24:25], v[8:9]
	v_and_b32_e32 v27, 0xffff0000, v42
	v_pk_add_f32 v[6:7], v[8:9], v[6:7]
	v_lshlrev_b32_e32 v26, 16, v42
	v_pk_add_f32 v[150:151], v[8:9], v[6:7] op_sel:[1,0] op_sel_hi:[0,1]
	v_and_b32_e32 v7, 0xffff0000, v77
	v_and_b32_e32 v6, 0xffff0000, v76
	v_pk_mul_f32 v[8:9], v[6:7], v[6:7]
	v_mul_f32_e32 v0, v27, v27
	v_pk_fma_f32 v[8:9], v[12:13], v[12:13], v[8:9]
	v_and_b32_e32 v29, 0xffff0000, v43
	v_pk_add_f32 v[10:11], v[8:9], v[8:9] op_sel:[0,1] op_sel_hi:[1,0]
	v_and_b32_e32 v9, 0xffff0000, v79
	v_and_b32_e32 v8, 0xffff0000, v78
	ds_read_b128 v[76:79], v75 offset:96
	s_lshl_b32 s98, s44, 9
	s_add_i32 s98, s98, 0x23000
	v_add_u32_e32 v204, s98, v61
	ds_read_b128 v[138:141], v204 offset:16
	ds_read_b128 v[142:145], v204
	v_pk_mul_f32 v[14:15], v[8:9], v[8:9]
	v_pk_fma_f32 v[146:147], v[26:27], v[26:27], v[0:1] op_sel_hi:[1,1,0]
	v_pk_fma_f32 v[14:15], v[20:21], v[20:21], v[14:15]
	v_lshlrev_b32_e32 v28, 16, v43
	v_pk_add_f32 v[10:11], v[14:15], v[10:11]
	v_mul_f32_e32 v0, v29, v29
	v_pk_add_f32 v[152:153], v[14:15], v[10:11] op_sel:[1,0] op_sel_hi:[0,1]
	s_waitcnt lgkmcnt(0)
	v_and_b32_e32 v11, 0xffff0000, v76
	v_pk_fma_f32 v[148:149], v[28:29], v[28:29], v[0:1] op_sel_hi:[1,1,0]
	v_lshlrev_b32_e32 v10, 16, v76
	v_mul_f32_e32 v0, v11, v11
	v_and_b32_e32 v15, 0xffff0000, v77
	v_pk_fma_f32 v[154:155], v[10:11], v[10:11], v[0:1] op_sel_hi:[1,1,0]
	v_lshlrev_b32_e32 v14, 16, v77
	v_mul_f32_e32 v0, v15, v15
	v_and_b32_e32 v157, 0xffff0000, v41
	v_and_b32_e32 v161, 0xffff0000, v40
	v_and_b32_e32 v165, 0xffff0000, v38
	v_pk_fma_f32 v[76:77], v[14:15], v[14:15], v[0:1] op_sel_hi:[1,1,0]
	v_lshlrev_b32_e32 v156, 16, v41
	v_mul_f32_e32 v0, v157, v157
	v_lshlrev_b32_e32 v160, 16, v40
	v_and_b32_e32 v163, 0xffff0000, v39
	v_lshlrev_b32_e32 v164, 16, v38
	v_mov_b32_e32 v42, v161
	v_mov_b32_e32 v43, v165
	v_pk_fma_f32 v[158:159], v[156:157], v[156:157], v[0:1] op_sel_hi:[1,1,0]
	v_lshlrev_b32_e32 v162, 16, v39
	v_mul_f32_e32 v0, v163, v163
	v_mov_b32_e32 v38, v160
	v_mov_b32_e32 v39, v164
	v_pk_mul_f32 v[42:43], v[42:43], v[42:43]
	v_pk_fma_f32 v[40:41], v[162:163], v[162:163], v[0:1] op_sel_hi:[1,1,0]
	v_pk_fma_f32 v[38:39], v[38:39], v[38:39], v[42:43]
	v_lshlrev_b32_e32 v173, 16, v4
	v_pk_add_f32 v[40:41], v[38:39], v[40:41] op_sel:[1,0] op_sel_hi:[0,1]
	v_pk_add_f32 v[166:167], v[38:39], v[40:41]
	v_pk_mov_b32 v[38:39], v[44:45], v[4:5] op_sel:[1,0]
	v_lshlrev_b32_e32 v182, 16, v5
	v_and_b32_e32 v5, 0xffff0000, v5
	v_and_b32_e32 v4, s0, v4
	v_pk_mul_f32 v[184:185], v[4:5], v[4:5]
	v_pk_add_f32 v[158:159], v[158:159], v[166:167]
	v_mov_b32_e32 v63, v185
	v_mul_f32_e32 v159, v182, v182
	v_pk_add_f32 v[62:63], v[158:159], v[62:63]
	v_lshlrev_b32_e32 v158, 16, v3
	v_and_b32_e32 v159, 0xffff0000, v3
	v_lshlrev_b32_e32 v169, 16, v2
	v_and_b32_e32 v171, 0xffff0000, v2
	v_and_b32_e32 v170, 0xffff0000, v44
	v_pk_mul_f32 v[2:3], v[158:159], v[158:159]
	v_lshlrev_b32_e32 v168, 16, v44
	v_and_b32_e32 v175, 0xffff0000, v39
	v_and_b32_e32 v174, 0xffff0000, v38
	v_pk_mul_f32 v[38:39], v[170:171], v[170:171]
	v_mov_b32_e32 v147, v2
	v_mov_b32_e32 v149, v3
	v_lshlrev_b32_e32 v172, 16, v45
	v_pk_fma_f32 v[176:177], v[168:169], v[168:169], v[38:39]
	v_pk_mul_f32 v[38:39], v[174:175], v[174:175]
	v_pk_add_f32 v[2:3], v[146:147], v[148:149]
	v_pk_fma_f32 v[178:179], v[172:173], v[172:173], v[38:39]
	v_pk_add_f32 v[2:3], v[176:177], v[2:3]
	v_lshlrev_b32_e32 v146, 16, v135
	v_pk_add_f32 v[2:3], v[178:179], v[2:3]
	v_and_b32_e32 v147, 0xffff0000, v135
	v_lshlrev_b32_e32 v41, 16, v134
	v_and_b32_e32 v39, 0xffff0000, v134
	v_and_b32_e32 v38, 0xffff0000, v78
	v_pk_mov_b32 v[42:43], v[78:79], v[136:137] op_sel:[1,0]
	v_pk_add_f32 v[2:3], v[62:63], v[2:3]
	v_pk_mul_f32 v[134:135], v[146:147], v[146:147]
	v_lshlrev_b32_e32 v40, 16, v78
	v_lshlrev_b32_e32 v44, 16, v79
	v_and_b32_e32 v43, 0xffff0000, v43
	v_and_b32_e32 v42, 0xffff0000, v42
	v_pk_mul_f32 v[78:79], v[38:39], v[38:39]
	v_pk_add_f32 v[62:63], v[2:3], v[2:3] op_sel:[0,1] op_sel_hi:[1,0]
	v_mov_b32_e32 v155, v134
	v_mov_b32_e32 v77, v135
	v_lshlrev_b32_e32 v45, 16, v136
	v_pk_fma_f32 v[78:79], v[40:41], v[40:41], v[78:79]
	v_pk_mul_f32 v[180:181], v[42:43], v[42:43]
	v_lshlrev_b32_e32 v2, 16, v137
	v_and_b32_e32 v3, 0xffff0000, v137
	v_pk_add_f32 v[62:63], v[62:63], v[150:151]
	v_pk_add_f32 v[76:77], v[154:155], v[76:77]
	v_pk_fma_f32 v[180:181], v[44:45], v[44:45], v[180:181]
	v_mul_f32_e32 v153, v3, v3
	v_mul_f32_e32 v63, v2, v2
	v_pk_add_f32 v[76:77], v[78:79], v[76:77]
	v_pk_add_f32 v[62:63], v[62:63], v[152:153]
	v_pk_add_f32 v[76:77], v[180:181], v[76:77]
	s_lshl_b64 s[0:1], s[74:75], 1
	v_pk_add_f32 v[62:63], v[62:63], v[76:77]
	s_add_u32 s0, s89, s0
	v_add_f32_e32 v4, v62, v63
	ds_bpermute_b32 v62, v232, v4
	s_addc_u32 s1, s86, s1
	v_lshlrev_b32_e32 v0, 11, v47
	v_mov_b32_e32 v47, v1
	v_mov_b32_e32 v183, v5
	s_waitcnt lgkmcnt(0)
	v_add_f32_e32 v4, v4, v62
	v_fmamk_f32 v4, v4, 0x3c000000, v230
	v_rsq_f32_e32 v4, v4
	v_lshl_add_u64 v[62:63], s[0:1], 0, v[0:1]
	v_lshl_add_u64 v[46:47], v[62:63], 0, v[46:47]
	s_mov_b64 s[0:1], 0
	v_mul_f32_e32 v0, 0x3f4ccccd, v4
	v_pk_mul_f32 v[62:63], v[0:1], v[164:165] op_sel_hi:[0,1]
	s_waitcnt lgkmcnt(0)
	v_pk_mul_f32 v[62:63], v[142:143], v[62:63]
	v_pk_mul_f32 v[26:27], v[0:1], v[26:27] op_sel_hi:[0,1]
	v_cvt_pk_bf16_f32 v76, v62, v63
	v_pk_mul_f32 v[62:63], v[0:1], v[162:163] op_sel_hi:[0,1]
	v_pk_mul_f32 v[62:63], v[144:145], v[62:63]
	v_pk_mul_f32 v[28:29], v[0:1], v[28:29] op_sel_hi:[0,1]
	v_cvt_pk_bf16_f32 v77, v62, v63
	v_pk_mul_f32 v[62:63], v[0:1], v[160:161] op_sel_hi:[0,1]
	v_pk_mul_f32 v[62:63], v[138:139], v[62:63]
	v_mov_b32_e32 v138, v36
	v_cvt_pk_bf16_f32 v78, v62, v63
	v_pk_mul_f32 v[62:63], v[0:1], v[156:157] op_sel_hi:[0,1]
	v_pk_mul_f32 v[62:63], v[140:141], v[62:63]
	v_mov_b32_e32 v139, v32
	v_cvt_pk_bf16_f32 v79, v62, v63
	global_store_dwordx4 v[46:47], v[76:79], off
	ds_read_b128 v[76:79], v204 offset:32
	s_nop 0
	ds_read_b128 v[134:137], v204 offset:48
	v_mov_b32_e32 v62, v34
	v_mov_b32_e32 v63, v30
	v_mov_b32_e32 v30, v35
	v_pk_mul_f32 v[34:35], v[0:1], v[62:63] op_sel_hi:[0,1]
	v_pk_mul_f32 v[30:31], v[0:1], v[30:31] op_sel_hi:[0,1]
	v_mov_b32_e32 v32, v37
	v_mov_b32_e32 v62, v168
	v_mov_b32_e32 v63, v170
	v_mov_b32_e32 v170, v169
	v_pk_mul_f32 v[4:5], v[0:1], v[170:171] op_sel_hi:[0,1]
	v_pk_mul_f32 v[10:11], v[0:1], v[10:11] op_sel_hi:[0,1]
	v_pk_mul_f32 v[14:15], v[0:1], v[14:15] op_sel_hi:[0,1]
	v_pk_mul_f32 v[2:3], v[0:1], v[2:3] op_sel_hi:[0,1]
	s_waitcnt lgkmcnt(1)
	v_pk_mul_f32 v[34:35], v[76:77], v[34:35]
	v_pk_mul_f32 v[30:31], v[78:79], v[30:31]
	v_cvt_pk_bf16_f32 v34, v34, v35
	v_cvt_pk_bf16_f32 v35, v30, v31
	v_pk_mul_f32 v[30:31], v[0:1], v[138:139] op_sel_hi:[0,1]
	s_waitcnt lgkmcnt(0)
	v_pk_mul_f32 v[30:31], v[30:31], v[134:135]
	v_mov_b32_e32 v76, v172
	v_cvt_pk_bf16_f32 v36, v30, v31
	v_pk_mul_f32 v[30:31], v[0:1], v[32:33] op_sel_hi:[0,1]
	v_pk_mul_f32 v[30:31], v[30:31], v[136:137]
	v_mov_b32_e32 v77, v174
	v_cvt_pk_bf16_f32 v37, v30, v31
	global_store_dwordx4 v[46:47], v[34:37], off offset:16
	ds_read_b128 v[30:33], v204 offset:64
	s_nop 0
	ds_read_b128 v[34:37], v204 offset:80
	v_mov_b32_e32 v174, v173
	s_waitcnt lgkmcnt(1)
	v_pk_mul_f32 v[26:27], v[26:27], v[30:31]
	v_pk_mul_f32 v[28:29], v[28:29], v[32:33]
	v_cvt_pk_bf16_f32 v26, v26, v27
	v_cvt_pk_bf16_f32 v27, v28, v29
	v_pk_mul_f32 v[28:29], v[0:1], v[62:63] op_sel_hi:[0,1]
	v_pk_mul_f32 v[30:31], v[0:1], v[76:77] op_sel_hi:[0,1]
	s_waitcnt lgkmcnt(0)
	v_pk_mul_f32 v[28:29], v[28:29], v[34:35]
	v_pk_mul_f32 v[30:31], v[30:31], v[36:37]
	v_cvt_pk_bf16_f32 v28, v28, v29
	v_cvt_pk_bf16_f32 v29, v30, v31
	global_store_dwordx4 v[46:47], v[26:29], off offset:32
	ds_read_b128 v[26:29], v204 offset:96
	s_nop 0
	ds_read_b128 v[30:33], v204 offset:112
	v_mov_b32_e32 v34, v24
	v_mov_b32_e32 v35, v18
	v_mov_b32_e32 v18, v25
	s_waitcnt lgkmcnt(1)
	v_pk_mul_f32 v[4:5], v[4:5], v[26:27]
	s_nop 0
	v_cvt_pk_bf16_f32 v26, v4, v5
	v_pk_mul_f32 v[4:5], v[0:1], v[158:159] op_sel_hi:[0,1]
	v_pk_mul_f32 v[4:5], v[4:5], v[28:29]
	s_nop 0
	v_cvt_pk_bf16_f32 v27, v4, v5
	v_pk_mul_f32 v[4:5], v[0:1], v[174:175] op_sel_hi:[0,1]
	s_waitcnt lgkmcnt(0)
	v_pk_mul_f32 v[4:5], v[4:5], v[30:31]
	s_nop 0
	v_cvt_pk_bf16_f32 v28, v4, v5
	v_pk_mul_f32 v[4:5], v[0:1], v[182:183] op_sel_hi:[0,1]
	v_pk_mul_f32 v[4:5], v[4:5], v[32:33]
	s_nop 0
	v_cvt_pk_bf16_f32 v29, v4, v5
	global_store_dwordx4 v[46:47], v[26:29], off offset:48
	ds_read_b128 v[26:29], v204 offset:128
	s_nop 0
	ds_read_b128 v[30:33], v204 offset:144
	v_mov_b32_e32 v4, v22
	v_mov_b32_e32 v5, v16
	v_pk_mul_f32 v[4:5], v[0:1], v[4:5] op_sel_hi:[0,1]
	v_mov_b32_e32 v16, v23
	s_waitcnt lgkmcnt(1)
	v_pk_mul_f32 v[4:5], v[4:5], v[26:27]
	s_nop 0
	v_cvt_pk_bf16_f32 v22, v4, v5
	v_pk_mul_f32 v[4:5], v[0:1], v[16:17] op_sel_hi:[0,1]
	v_pk_mul_f32 v[4:5], v[4:5], v[28:29]
	s_nop 0
	v_cvt_pk_bf16_f32 v23, v4, v5
	v_pk_mul_f32 v[4:5], v[0:1], v[34:35] op_sel_hi:[0,1]
	s_waitcnt lgkmcnt(0)
	v_pk_mul_f32 v[4:5], v[4:5], v[30:31]
	s_nop 0
	v_cvt_pk_bf16_f32 v24, v4, v5
	v_pk_mul_f32 v[4:5], v[0:1], v[18:19] op_sel_hi:[0,1]
	v_pk_mul_f32 v[4:5], v[4:5], v[32:33]
	s_nop 0
	v_cvt_pk_bf16_f32 v25, v4, v5
	global_store_dwordx4 v[46:47], v[22:25], off offset:64
	ds_read_b128 v[16:19], v204 offset:160
	s_nop 0
	ds_read_b128 v[22:25], v204 offset:176
	v_mov_b32_e32 v4, v12
	v_mov_b32_e32 v5, v6
	v_mov_b32_e32 v6, v13
	v_mov_b32_e32 v12, v20
	v_mov_b32_e32 v13, v8
	v_mov_b32_e32 v8, v21
	v_pk_mul_f32 v[4:5], v[0:1], v[4:5] op_sel_hi:[0,1]
	v_pk_mul_f32 v[6:7], v[0:1], v[6:7] op_sel_hi:[0,1]
	v_pk_mul_f32 v[12:13], v[0:1], v[12:13] op_sel_hi:[0,1]
	v_pk_mul_f32 v[8:9], v[0:1], v[8:9] op_sel_hi:[0,1]
	s_waitcnt lgkmcnt(1)
	v_pk_mul_f32 v[4:5], v[4:5], v[16:17]
	v_pk_mul_f32 v[6:7], v[6:7], v[18:19]
	s_waitcnt lgkmcnt(0)
	v_pk_mul_f32 v[12:13], v[12:13], v[22:23]
	v_pk_mul_f32 v[8:9], v[8:9], v[24:25]
	v_cvt_pk_bf16_f32 v4, v4, v5
	v_cvt_pk_bf16_f32 v5, v6, v7
	v_cvt_pk_bf16_f32 v6, v12, v13
	v_cvt_pk_bf16_f32 v7, v8, v9
	global_store_dwordx4 v[46:47], v[4:7], off offset:80
	ds_read_b128 v[4:7], v204 offset:192
	s_nop 0
	ds_read_b128 v[16:19], v204 offset:208
	v_mov_b32_e32 v8, v40
	v_mov_b32_e32 v9, v38
	v_mov_b32_e32 v12, v44
	v_mov_b32_e32 v13, v42
	v_pk_mul_f32 v[8:9], v[0:1], v[8:9] op_sel_hi:[0,1]
	v_pk_mul_f32 v[12:13], v[0:1], v[12:13] op_sel_hi:[0,1]
	v_mov_b32_e32 v38, v41
	v_mov_b32_e32 v42, v45
	s_waitcnt lgkmcnt(1)
	v_pk_mul_f32 v[4:5], v[10:11], v[4:5]
	v_pk_mul_f32 v[6:7], v[14:15], v[6:7]
	s_waitcnt lgkmcnt(0)
	v_pk_mul_f32 v[8:9], v[8:9], v[16:17]
	v_pk_mul_f32 v[10:11], v[12:13], v[18:19]
	v_cvt_pk_bf16_f32 v4, v4, v5
	v_cvt_pk_bf16_f32 v5, v6, v7
	v_cvt_pk_bf16_f32 v6, v8, v9
	v_cvt_pk_bf16_f32 v7, v10, v11
	global_store_dwordx4 v[46:47], v[4:7], off offset:96
	ds_read_b128 v[4:7], v204 offset:224
	s_nop 0
	ds_read_b128 v[8:11], v204 offset:240
	v_pk_mul_f32 v[12:13], v[0:1], v[38:39] op_sel_hi:[0,1]
	v_pk_mul_f32 v[14:15], v[0:1], v[146:147] op_sel_hi:[0,1]
	v_pk_mul_f32 v[16:17], v[0:1], v[42:43] op_sel_hi:[0,1]
	s_waitcnt lgkmcnt(1)
	v_pk_mul_f32 v[4:5], v[12:13], v[4:5]
	v_pk_mul_f32 v[6:7], v[14:15], v[6:7]
	s_waitcnt lgkmcnt(0)
	v_pk_mul_f32 v[8:9], v[16:17], v[8:9]
	v_pk_mul_f32 v[10:11], v[2:3], v[10:11]
	v_cvt_pk_bf16_f32 v2, v4, v5
	v_cvt_pk_bf16_f32 v3, v6, v7
	v_cvt_pk_bf16_f32 v4, v8, v9
	v_cvt_pk_bf16_f32 v5, v10, v11
	global_store_dwordx4 v[46:47], v[2:5], off offset:112
